# v32 plus loop-invariant LDS fragment-read base addresses computed once before each GEMM K loop
# baseline (speedup 1.0000x reference)
.LBB0_232:
	s_ashr_i32 s25, s24, 31
	s_lshl_b64 s[26:27], s[24:25], 21
	s_add_u32 s26, s46, s26
	s_addc_u32 s27, s47, s27
	s_and_b64 s[28:29], s[2:3], exec
	s_cselect_b32 s25, s27, s35
	s_cselect_b32 s64, s26, s34
	s_ashr_i32 s23, s22, 31
	s_lshl_b64 s[28:29], s[22:23], 21
	s_add_u32 s28, s48, s28
	s_addc_u32 s29, s49, s29
	s_and_b64 s[38:39], s[2:3], exec
	s_cselect_b32 s23, s29, s37
	s_cselect_b32 s65, s28, s36
	s_add_u32 s66, s36, 0x100
	s_addc_u32 s67, s37, 0
	s_add_u32 s34, s34, 0x100080
	v_mov_b64_e32 v[0:1], 0
	s_addc_u32 s35, s35, 0
	s_mov_b32 s68, -2
	v_mov_b64_e32 v[2:3], 0
	v_mov_b64_e32 v[4:5], 0
	v_mov_b64_e32 v[6:7], 0
	v_mov_b64_e32 v[12:13], 0
	v_mov_b64_e32 v[14:15], 0
	v_mov_b64_e32 v[20:21], 0
	v_mov_b64_e32 v[22:23], 0
	v_mov_b64_e32 v[28:29], 0
	v_mov_b64_e32 v[30:31], 0
	v_mov_b64_e32 v[36:37], 0
	v_mov_b64_e32 v[38:39], 0
	v_mov_b64_e32 v[44:45], 0
	v_mov_b64_e32 v[46:47], 0
	v_mov_b64_e32 v[52:53], 0
	v_mov_b64_e32 v[54:55], 0
	v_mov_b64_e32 v[8:9], 0
	v_mov_b64_e32 v[10:11], 0
	v_mov_b64_e32 v[16:17], 0
	v_mov_b64_e32 v[18:19], 0
	v_mov_b64_e32 v[24:25], 0
	v_mov_b64_e32 v[26:27], 0
	v_mov_b64_e32 v[32:33], 0
	v_mov_b64_e32 v[34:35], 0
	v_mov_b64_e32 v[40:41], 0
	v_mov_b64_e32 v[42:43], 0
	v_mov_b64_e32 v[48:49], 0
	v_mov_b64_e32 v[50:51], 0
	v_mov_b64_e32 v[56:57], 0
	v_mov_b64_e32 v[58:59], 0
	v_mov_b64_e32 v[60:61], 0
	v_mov_b64_e32 v[62:63], 0
	v_mov_b64_e32 v[64:65], 0
	v_mov_b64_e32 v[66:67], 0
	v_mov_b64_e32 v[68:69], 0
	v_mov_b64_e32 v[70:71], 0
	v_mov_b64_e32 v[80:81], 0
	v_mov_b64_e32 v[82:83], 0
	v_mov_b64_e32 v[84:85], 0
	v_mov_b64_e32 v[86:87], 0
	v_mov_b64_e32 v[96:97], 0
	v_mov_b64_e32 v[98:99], 0
	v_mov_b64_e32 v[100:101], 0
	v_mov_b64_e32 v[102:103], 0
	v_mov_b64_e32 v[112:113], 0
	v_mov_b64_e32 v[114:115], 0
	v_mov_b64_e32 v[116:117], 0
	v_mov_b64_e32 v[118:119], 0
	v_mov_b64_e32 v[72:73], 0
	v_mov_b64_e32 v[74:75], 0
	v_mov_b64_e32 v[76:77], 0
	v_mov_b64_e32 v[78:79], 0
	v_mov_b64_e32 v[88:89], 0
	v_mov_b64_e32 v[90:91], 0
	v_mov_b64_e32 v[92:93], 0
	v_mov_b64_e32 v[94:95], 0
	v_mov_b64_e32 v[104:105], 0
	v_mov_b64_e32 v[106:107], 0
	v_mov_b64_e32 v[108:109], 0
	v_mov_b64_e32 v[110:111], 0
	v_mov_b64_e32 v[120:121], 0
	v_mov_b64_e32 v[122:123], 0
	v_mov_b64_e32 v[124:125], 0
	v_mov_b64_e32 v[126:127], 0
	v_add_u32_e32 v248, 0x18000, v149
	v_add_u32_e32 v249, 0x1c000, v149
	s_cmp_lt_u32 s81, 4
	s_cbranch_scc0 .Lsp_skip0
	s_setprio 1

.LBB0_253:
	s_add_u32 s65, s26, 0x100
	v_mov_b64_e32 v[0:1], 0
	s_addc_u32 s66, s27, 0
	s_mov_b32 s67, -2
	v_mov_b64_e32 v[2:3], 0
	v_mov_b64_e32 v[4:5], 0
	v_mov_b64_e32 v[6:7], 0
	v_mov_b64_e32 v[8:9], 0
	v_mov_b64_e32 v[10:11], 0
	v_mov_b64_e32 v[16:17], 0
	v_mov_b64_e32 v[18:19], 0
	v_mov_b64_e32 v[24:25], 0
	v_mov_b64_e32 v[26:27], 0
	v_mov_b64_e32 v[32:33], 0
	v_mov_b64_e32 v[34:35], 0
	v_mov_b64_e32 v[40:41], 0
	v_mov_b64_e32 v[42:43], 0
	v_mov_b64_e32 v[48:49], 0
	v_mov_b64_e32 v[50:51], 0
	v_mov_b64_e32 v[12:13], 0
	v_mov_b64_e32 v[14:15], 0
	v_mov_b64_e32 v[20:21], 0
	v_mov_b64_e32 v[22:23], 0
	v_mov_b64_e32 v[28:29], 0
	v_mov_b64_e32 v[30:31], 0
	v_mov_b64_e32 v[36:37], 0
	v_mov_b64_e32 v[38:39], 0
	v_mov_b64_e32 v[44:45], 0
	v_mov_b64_e32 v[46:47], 0
	v_mov_b64_e32 v[52:53], 0
	v_mov_b64_e32 v[54:55], 0
	v_mov_b64_e32 v[56:57], 0
	v_mov_b64_e32 v[58:59], 0
	v_mov_b64_e32 v[60:61], 0
	v_mov_b64_e32 v[62:63], 0
	v_mov_b64_e32 v[64:65], 0
	v_mov_b64_e32 v[66:67], 0
	v_mov_b64_e32 v[68:69], 0
	v_mov_b64_e32 v[70:71], 0
	v_mov_b64_e32 v[72:73], 0
	v_mov_b64_e32 v[74:75], 0
	v_mov_b64_e32 v[80:81], 0
	v_mov_b64_e32 v[82:83], 0
	v_mov_b64_e32 v[88:89], 0
	v_mov_b64_e32 v[90:91], 0
	v_mov_b64_e32 v[96:97], 0
	v_mov_b64_e32 v[98:99], 0
	v_mov_b64_e32 v[104:105], 0
	v_mov_b64_e32 v[106:107], 0
	v_mov_b64_e32 v[112:113], 0
	v_mov_b64_e32 v[114:115], 0
	v_mov_b64_e32 v[76:77], 0
	v_mov_b64_e32 v[78:79], 0
	v_mov_b64_e32 v[84:85], 0
	v_mov_b64_e32 v[86:87], 0
	v_mov_b64_e32 v[92:93], 0
	v_mov_b64_e32 v[94:95], 0
	v_mov_b64_e32 v[100:101], 0
	v_mov_b64_e32 v[102:103], 0
	v_mov_b64_e32 v[108:109], 0
	v_mov_b64_e32 v[110:111], 0
	v_mov_b64_e32 v[116:117], 0
	v_mov_b64_e32 v[118:119], 0
	v_mov_b64_e32 v[120:121], 0
	v_mov_b64_e32 v[122:123], 0
	v_mov_b64_e32 v[124:125], 0
	v_mov_b64_e32 v[126:127], 0
	v_add_u32_e32 v248, 0x18000, v147
	v_add_u32_e32 v249, 0x1c000, v147
	s_cmp_lt_u32 s81, 4
	s_cbranch_scc0 .Lsp_skip1
	s_setprio 1

.LBB0_280:
	s_ashr_i32 s23, s22, 31
	s_lshl_b64 s[24:25], s[22:23], 20
	s_add_u32 s24, s39, s24
	s_addc_u32 s25, s45, s25
	s_and_b64 s[26:27], s[2:3], exec
	s_cselect_b32 s23, s25, s35
	s_cselect_b32 s57, s24, s34
	s_ashr_i32 s21, s20, 31
	s_lshl_b64 s[26:27], s[20:21], 20
	s_add_u32 s26, s46, s26
	s_addc_u32 s27, s47, s27
	s_and_b64 s[36:37], s[2:3], exec
	s_cselect_b32 s21, s27, s31
	s_cselect_b32 s58, s26, s30
	s_add_u32 s59, s30, 0x100
	s_addc_u32 s60, s31, 0
	s_add_u32 s30, s34, 0x80080
	v_mov_b64_e32 v[0:1], 0
	s_addc_u32 s31, s35, 0
	s_mov_b32 s61, -2
	v_mov_b64_e32 v[2:3], 0
	v_mov_b64_e32 v[4:5], 0
	v_mov_b64_e32 v[6:7], 0
	v_mov_b64_e32 v[16:17], 0
	v_mov_b64_e32 v[18:19], 0
	v_mov_b64_e32 v[20:21], 0
	v_mov_b64_e32 v[22:23], 0
	v_mov_b64_e32 v[32:33], 0
	v_mov_b64_e32 v[34:35], 0
	v_mov_b64_e32 v[36:37], 0
	v_mov_b64_e32 v[38:39], 0
	v_mov_b64_e32 v[48:49], 0
	v_mov_b64_e32 v[50:51], 0
	v_mov_b64_e32 v[52:53], 0
	v_mov_b64_e32 v[54:55], 0
	v_mov_b64_e32 v[8:9], 0
	v_mov_b64_e32 v[10:11], 0
	v_mov_b64_e32 v[12:13], 0
	v_mov_b64_e32 v[14:15], 0
	v_mov_b64_e32 v[24:25], 0
	v_mov_b64_e32 v[26:27], 0
	v_mov_b64_e32 v[28:29], 0
	v_mov_b64_e32 v[30:31], 0
	v_mov_b64_e32 v[40:41], 0
	v_mov_b64_e32 v[42:43], 0
	v_mov_b64_e32 v[44:45], 0
	v_mov_b64_e32 v[46:47], 0
	v_mov_b64_e32 v[56:57], 0
	v_mov_b64_e32 v[58:59], 0
	v_mov_b64_e32 v[60:61], 0
	v_mov_b64_e32 v[62:63], 0
	v_mov_b64_e32 v[64:65], 0
	v_mov_b64_e32 v[66:67], 0
	v_mov_b64_e32 v[68:69], 0
	v_mov_b64_e32 v[70:71], 0
	v_mov_b64_e32 v[80:81], 0
	v_mov_b64_e32 v[82:83], 0
	v_mov_b64_e32 v[84:85], 0
	v_mov_b64_e32 v[86:87], 0
	v_mov_b64_e32 v[96:97], 0
	v_mov_b64_e32 v[98:99], 0
	v_mov_b64_e32 v[100:101], 0
	v_mov_b64_e32 v[102:103], 0
	v_mov_b64_e32 v[112:113], 0
	v_mov_b64_e32 v[114:115], 0
	v_mov_b64_e32 v[116:117], 0
	v_mov_b64_e32 v[118:119], 0
	v_mov_b64_e32 v[72:73], 0
	v_mov_b64_e32 v[74:75], 0
	v_mov_b64_e32 v[76:77], 0
	v_mov_b64_e32 v[78:79], 0
	v_mov_b64_e32 v[88:89], 0
	v_mov_b64_e32 v[90:91], 0
	v_mov_b64_e32 v[92:93], 0
	v_mov_b64_e32 v[94:95], 0
	v_mov_b64_e32 v[104:105], 0
	v_mov_b64_e32 v[106:107], 0
	v_mov_b64_e32 v[108:109], 0
	v_mov_b64_e32 v[110:111], 0
	v_mov_b64_e32 v[120:121], 0
	v_mov_b64_e32 v[122:123], 0
	v_mov_b64_e32 v[124:125], 0
	v_mov_b64_e32 v[126:127], 0
	v_add_u32_e32 v248, 0x18000, v151
	v_add_u32_e32 v249, 0x1c000, v151
	s_cmp_lt_u32 s81, 4
	s_cbranch_scc0 .Lsp_skip2
	s_setprio 1

.LBB0_450:
	s_ashr_i32 s21, s20, 31
	s_lshl_b64 s[22:23], s[20:21], 21
	s_add_u32 s22, s33, s22
	s_addc_u32 s23, s38, s23
	s_and_b64 s[24:25], s[4:5], exec
	s_cselect_b32 s21, s23, s35
	s_cselect_b32 s27, s22, s34
	s_ashr_i32 s19, s18, 31
	s_lshl_b64 s[24:25], s[18:19], 21
	s_add_u32 s24, s39, s24
	s_addc_u32 s25, s40, s25
	s_and_b64 s[36:37], s[4:5], exec
	s_cselect_b32 s19, s25, s31
	s_cselect_b32 s55, s24, s30
	s_add_u32 s56, s30, 0x100
	s_addc_u32 s57, s31, 0
	s_add_u32 s30, s34, 0x100080
	v_mov_b64_e32 v[0:1], 0
	s_addc_u32 s31, s35, 0
	s_mov_b32 s58, -2
	s_waitcnt lgkmcnt(0)
	v_mov_b64_e32 v[2:3], 0
	v_mov_b64_e32 v[4:5], 0
	v_mov_b64_e32 v[6:7], 0
	v_mov_b64_e32 v[16:17], 0
	v_mov_b64_e32 v[18:19], 0
	v_mov_b64_e32 v[20:21], 0
	v_mov_b64_e32 v[22:23], 0
	v_mov_b64_e32 v[32:33], 0
	v_mov_b64_e32 v[34:35], 0
	v_mov_b64_e32 v[36:37], 0
	v_mov_b64_e32 v[38:39], 0
	v_mov_b64_e32 v[48:49], 0
	v_mov_b64_e32 v[50:51], 0
	v_mov_b64_e32 v[52:53], 0
	v_mov_b64_e32 v[54:55], 0
	v_mov_b64_e32 v[8:9], 0
	v_mov_b64_e32 v[10:11], 0
	v_mov_b64_e32 v[12:13], 0
	v_mov_b64_e32 v[14:15], 0
	v_mov_b64_e32 v[24:25], 0
	v_mov_b64_e32 v[26:27], 0
	v_mov_b64_e32 v[28:29], 0
	v_mov_b64_e32 v[30:31], 0
	v_mov_b64_e32 v[40:41], 0
	v_mov_b64_e32 v[42:43], 0
	v_mov_b64_e32 v[44:45], 0
	v_mov_b64_e32 v[46:47], 0
	v_mov_b64_e32 v[56:57], 0
	v_mov_b64_e32 v[58:59], 0
	v_mov_b64_e32 v[60:61], 0
	v_mov_b64_e32 v[62:63], 0
	v_mov_b64_e32 v[64:65], 0
	v_mov_b64_e32 v[66:67], 0
	v_mov_b64_e32 v[68:69], 0
	v_mov_b64_e32 v[70:71], 0
	v_mov_b64_e32 v[80:81], 0
	v_mov_b64_e32 v[82:83], 0
	v_mov_b64_e32 v[84:85], 0
	v_mov_b64_e32 v[86:87], 0
	v_mov_b64_e32 v[96:97], 0
	v_mov_b64_e32 v[98:99], 0
	v_mov_b64_e32 v[100:101], 0
	v_mov_b64_e32 v[102:103], 0
	v_mov_b64_e32 v[116:117], 0
	v_mov_b64_e32 v[118:119], 0
	v_mov_b64_e32 v[120:121], 0
	v_mov_b64_e32 v[122:123], 0
	v_mov_b64_e32 v[72:73], 0
	v_mov_b64_e32 v[74:75], 0
	v_mov_b64_e32 v[76:77], 0
	v_mov_b64_e32 v[78:79], 0
	v_mov_b64_e32 v[88:89], 0
	v_mov_b64_e32 v[90:91], 0
	v_mov_b64_e32 v[92:93], 0
	v_mov_b64_e32 v[94:95], 0
	v_mov_b64_e32 v[104:105], 0
	v_mov_b64_e32 v[106:107], 0
	v_mov_b64_e32 v[108:109], 0
	v_mov_b64_e32 v[110:111], 0
	v_mov_b64_e32 v[128:129], 0
	v_mov_b64_e32 v[130:131], 0
	v_mov_b64_e32 v[132:133], 0
	v_mov_b64_e32 v[134:135], 0
	v_add_u32_e32 v248, 0x18000, v191
	v_add_u32_e32 v249, 0x1c000, v191
	s_cmp_lt_u32 s81, 4
	s_cbranch_scc0 .Lsp_skip3
	s_setprio 1

.LBB0_549:
	s_ashr_i32 s31, s30, 31
	s_lshl_b64 s[34:35], s[30:31], 20
	s_add_u32 s34, s40, s34
	s_addc_u32 s35, s41, s35
	s_and_b64 s[36:37], s[2:3], exec
	s_cselect_b32 s1, s35, s7
	s_cselect_b32 s31, s34, s6
	s_ashr_i32 s29, s28, 31
	s_lshl_b64 s[36:37], s[28:29], 20
	s_add_u32 s36, s42, s36
	s_addc_u32 s37, s43, s37
	s_and_b64 s[38:39], s[2:3], exec
	s_cselect_b32 s29, s37, s5
	s_cselect_b32 s61, s36, s4
	s_add_u32 s62, s4, 0x100
	s_addc_u32 s63, s5, 0
	s_add_u32 s4, s6, 0x80080
	v_mov_b64_e32 v[0:1], 0
	s_addc_u32 s5, s7, 0
	s_mov_b32 s64, -2
	v_mov_b64_e32 v[2:3], 0
	v_mov_b64_e32 v[4:5], 0
	v_mov_b64_e32 v[6:7], 0
	v_mov_b64_e32 v[16:17], 0
	v_mov_b64_e32 v[18:19], 0
	v_mov_b64_e32 v[20:21], 0
	v_mov_b64_e32 v[22:23], 0
	v_mov_b64_e32 v[32:33], 0
	v_mov_b64_e32 v[34:35], 0
	v_mov_b64_e32 v[36:37], 0
	v_mov_b64_e32 v[38:39], 0
	v_mov_b64_e32 v[48:49], 0
	v_mov_b64_e32 v[50:51], 0
	v_mov_b64_e32 v[52:53], 0
	v_mov_b64_e32 v[54:55], 0
	v_mov_b64_e32 v[8:9], 0
	v_mov_b64_e32 v[10:11], 0
	v_mov_b64_e32 v[12:13], 0
	v_mov_b64_e32 v[14:15], 0
	v_mov_b64_e32 v[24:25], 0
	v_mov_b64_e32 v[26:27], 0
	v_mov_b64_e32 v[28:29], 0
	v_mov_b64_e32 v[30:31], 0
	v_mov_b64_e32 v[40:41], 0
	v_mov_b64_e32 v[42:43], 0
	v_mov_b64_e32 v[44:45], 0
	v_mov_b64_e32 v[46:47], 0
	v_mov_b64_e32 v[56:57], 0
	v_mov_b64_e32 v[58:59], 0
	v_mov_b64_e32 v[60:61], 0
	v_mov_b64_e32 v[62:63], 0
	v_mov_b64_e32 v[64:65], 0
	v_mov_b64_e32 v[66:67], 0
	v_mov_b64_e32 v[68:69], 0
	v_mov_b64_e32 v[70:71], 0
	v_mov_b64_e32 v[80:81], 0
	v_mov_b64_e32 v[82:83], 0
	v_mov_b64_e32 v[84:85], 0
	v_mov_b64_e32 v[86:87], 0
	v_mov_b64_e32 v[96:97], 0
	v_mov_b64_e32 v[98:99], 0
	v_mov_b64_e32 v[100:101], 0
	v_mov_b64_e32 v[102:103], 0
	v_mov_b64_e32 v[112:113], 0
	v_mov_b64_e32 v[114:115], 0
	v_mov_b64_e32 v[116:117], 0
	v_mov_b64_e32 v[118:119], 0
	v_mov_b64_e32 v[72:73], 0
	v_mov_b64_e32 v[74:75], 0
	v_mov_b64_e32 v[76:77], 0
	v_mov_b64_e32 v[78:79], 0
	v_mov_b64_e32 v[88:89], 0
	v_mov_b64_e32 v[90:91], 0
	v_mov_b64_e32 v[92:93], 0
	v_mov_b64_e32 v[94:95], 0
	v_mov_b64_e32 v[104:105], 0
	v_mov_b64_e32 v[106:107], 0
	v_mov_b64_e32 v[108:109], 0
	v_mov_b64_e32 v[110:111], 0
	v_mov_b64_e32 v[120:121], 0
	v_mov_b64_e32 v[122:123], 0
	v_mov_b64_e32 v[124:125], 0
	v_mov_b64_e32 v[126:127], 0
	v_add_u32_e32 v248, 0x18000, v157
	v_add_u32_e32 v249, 0x1c000, v157
	s_cmp_lt_u32 s81, 4
	s_cbranch_scc0 .Lsp_skip4
	s_setprio 1

.LBB0_634:
	s_ashr_i32 s21, s20, 31
	s_mul_i32 s22, s20, 0x810000
	s_mov_b32 s23, 0
	s_add_u32 s22, s33, s22
	s_addc_u32 s23, s38, s23
	s_and_b64 s[24:25], s[4:5], exec
	s_cselect_b32 s21, s23, s35
	s_cselect_b32 s27, s22, s34
	s_ashr_i32 s19, s18, 31
	s_lshl_b64 s[24:25], s[18:19], 23
	s_add_u32 s24, s39, s24
	s_addc_u32 s25, s40, s25
	s_and_b64 s[36:37], s[4:5], exec
	s_cselect_b32 s19, s25, s31
	s_cselect_b32 s55, s24, s30
	s_add_u32 s56, s30, 0x100
	s_addc_u32 s57, s31, 0
	s_add_u32 s30, s34, 0x408080
	v_mov_b64_e32 v[0:1], 0
	s_addc_u32 s31, s35, 0
	s_mov_b32 s58, -2
	s_waitcnt lgkmcnt(0)
	v_mov_b64_e32 v[2:3], 0
	v_mov_b64_e32 v[4:5], 0
	v_mov_b64_e32 v[6:7], 0
	v_mov_b64_e32 v[16:17], 0
	v_mov_b64_e32 v[18:19], 0
	v_mov_b64_e32 v[20:21], 0
	v_mov_b64_e32 v[22:23], 0
	v_mov_b64_e32 v[32:33], 0
	v_mov_b64_e32 v[34:35], 0
	v_mov_b64_e32 v[36:37], 0
	v_mov_b64_e32 v[38:39], 0
	v_mov_b64_e32 v[48:49], 0
	v_mov_b64_e32 v[50:51], 0
	v_mov_b64_e32 v[52:53], 0
	v_mov_b64_e32 v[54:55], 0
	v_mov_b64_e32 v[8:9], 0
	v_mov_b64_e32 v[10:11], 0
	v_mov_b64_e32 v[12:13], 0
	v_mov_b64_e32 v[14:15], 0
	v_mov_b64_e32 v[24:25], 0
	v_mov_b64_e32 v[26:27], 0
	v_mov_b64_e32 v[28:29], 0
	v_mov_b64_e32 v[30:31], 0
	v_mov_b64_e32 v[40:41], 0
	v_mov_b64_e32 v[42:43], 0
	v_mov_b64_e32 v[44:45], 0
	v_mov_b64_e32 v[46:47], 0
	v_mov_b64_e32 v[56:57], 0
	v_mov_b64_e32 v[58:59], 0
	v_mov_b64_e32 v[60:61], 0
	v_mov_b64_e32 v[62:63], 0
	v_mov_b64_e32 v[64:65], 0
	v_mov_b64_e32 v[66:67], 0
	v_mov_b64_e32 v[68:69], 0
	v_mov_b64_e32 v[70:71], 0
	v_mov_b64_e32 v[80:81], 0
	v_mov_b64_e32 v[82:83], 0
	v_mov_b64_e32 v[84:85], 0
	v_mov_b64_e32 v[86:87], 0
	v_mov_b64_e32 v[96:97], 0
	v_mov_b64_e32 v[98:99], 0
	v_mov_b64_e32 v[100:101], 0
	v_mov_b64_e32 v[102:103], 0
	v_mov_b64_e32 v[116:117], 0
	v_mov_b64_e32 v[118:119], 0
	v_mov_b64_e32 v[120:121], 0
	v_mov_b64_e32 v[122:123], 0
	v_mov_b64_e32 v[72:73], 0
	v_mov_b64_e32 v[74:75], 0
	v_mov_b64_e32 v[76:77], 0
	v_mov_b64_e32 v[78:79], 0
	v_mov_b64_e32 v[88:89], 0
	v_mov_b64_e32 v[90:91], 0
	v_mov_b64_e32 v[92:93], 0
	v_mov_b64_e32 v[94:95], 0
	v_mov_b64_e32 v[104:105], 0
	v_mov_b64_e32 v[106:107], 0
	v_mov_b64_e32 v[108:109], 0
	v_mov_b64_e32 v[110:111], 0
	v_mov_b64_e32 v[128:129], 0
	v_mov_b64_e32 v[130:131], 0
	v_mov_b64_e32 v[132:133], 0
	v_mov_b64_e32 v[134:135], 0
	v_add_u32_e32 v248, 0x18000, v191
	v_add_u32_e32 v249, 0x1c000, v191
	s_cmp_lt_u32 s81, 4
	s_cbranch_scc0 .Lsp_skip5
	s_setprio 1

.LBB0_725:
	s_ashr_i32 s23, s22, 31
	s_lshl_b64 s[24:25], s[22:23], 20
	s_add_u32 s24, s30, s24
	s_addc_u32 s25, s31, s25
	s_and_b64 s[26:27], s[2:3], exec
	s_cselect_b32 s1, s25, s7
	s_cselect_b32 s23, s24, s6
	s_ashr_i32 s21, s20, 31
	s_lshl_b64 s[26:27], s[20:21], 20
	s_add_u32 s26, s33, s26
	s_addc_u32 s27, s34, s27
	s_and_b64 s[28:29], s[2:3], exec
	s_cselect_b32 s21, s27, s5
	s_cselect_b32 s51, s26, s4
	s_add_u32 s52, s4, 0x100
	s_addc_u32 s53, s5, 0
	s_add_u32 s4, s6, 0x80080
	v_mov_b64_e32 v[0:1], 0
	s_addc_u32 s5, s7, 0
	s_mov_b32 s54, -2
	v_mov_b64_e32 v[2:3], 0
	v_mov_b64_e32 v[4:5], 0
	v_mov_b64_e32 v[6:7], 0
	v_mov_b64_e32 v[16:17], 0
	v_mov_b64_e32 v[18:19], 0
	v_mov_b64_e32 v[20:21], 0
	v_mov_b64_e32 v[22:23], 0
	v_mov_b64_e32 v[32:33], 0
	v_mov_b64_e32 v[34:35], 0
	v_mov_b64_e32 v[36:37], 0
	v_mov_b64_e32 v[38:39], 0
	v_mov_b64_e32 v[48:49], 0
	v_mov_b64_e32 v[50:51], 0
	v_mov_b64_e32 v[52:53], 0
	v_mov_b64_e32 v[54:55], 0
	v_mov_b64_e32 v[8:9], 0
	v_mov_b64_e32 v[10:11], 0
	v_mov_b64_e32 v[12:13], 0
	v_mov_b64_e32 v[14:15], 0
	v_mov_b64_e32 v[24:25], 0
	v_mov_b64_e32 v[26:27], 0
	v_mov_b64_e32 v[28:29], 0
	v_mov_b64_e32 v[30:31], 0
	v_mov_b64_e32 v[40:41], 0
	v_mov_b64_e32 v[42:43], 0
	v_mov_b64_e32 v[44:45], 0
	v_mov_b64_e32 v[46:47], 0
	v_mov_b64_e32 v[56:57], 0
	v_mov_b64_e32 v[58:59], 0
	v_mov_b64_e32 v[60:61], 0
	v_mov_b64_e32 v[62:63], 0
	v_mov_b64_e32 v[64:65], 0
	v_mov_b64_e32 v[66:67], 0
	v_mov_b64_e32 v[68:69], 0
	v_mov_b64_e32 v[70:71], 0
	v_mov_b64_e32 v[80:81], 0
	v_mov_b64_e32 v[82:83], 0
	v_mov_b64_e32 v[84:85], 0
	v_mov_b64_e32 v[86:87], 0
	v_mov_b64_e32 v[96:97], 0
	v_mov_b64_e32 v[98:99], 0
	v_mov_b64_e32 v[100:101], 0
	v_mov_b64_e32 v[102:103], 0
	v_mov_b64_e32 v[112:113], 0
	v_mov_b64_e32 v[114:115], 0
	v_mov_b64_e32 v[116:117], 0
	v_mov_b64_e32 v[118:119], 0
	v_mov_b64_e32 v[72:73], 0
	v_mov_b64_e32 v[74:75], 0
	v_mov_b64_e32 v[76:77], 0
	v_mov_b64_e32 v[78:79], 0
	v_mov_b64_e32 v[88:89], 0
	v_mov_b64_e32 v[90:91], 0
	v_mov_b64_e32 v[92:93], 0
	v_mov_b64_e32 v[94:95], 0
	v_mov_b64_e32 v[104:105], 0
	v_mov_b64_e32 v[106:107], 0
	v_mov_b64_e32 v[108:109], 0
	v_mov_b64_e32 v[110:111], 0
	v_mov_b64_e32 v[120:121], 0
	v_mov_b64_e32 v[122:123], 0
	v_mov_b64_e32 v[124:125], 0
	v_mov_b64_e32 v[126:127], 0
	v_add_u32_e32 v248, 0x18000, v157
	v_add_u32_e32 v249, 0x1c000, v157
	s_cmp_lt_u32 s81, 4
	s_cbranch_scc0 .Lsp_skip6
	s_setprio 1

.LBB0_1355:
	s_ashr_i32 s23, s22, 31
	s_lshl_b64 s[24:25], s[22:23], 20
	s_add_u32 s24, s38, s24
	s_addc_u32 s25, s39, s25
	s_and_b64 s[26:27], s[2:3], exec
	s_cselect_b32 s1, s25, s35
	s_cselect_b32 s23, s24, s34
	s_ashr_i32 s21, s20, 31
	s_lshl_b64 s[26:27], s[20:21], 20
	s_add_u32 s26, s40, s26
	s_addc_u32 s27, s41, s27
	s_and_b64 s[36:37], s[2:3], exec
	s_cselect_b32 s21, s27, s31
	s_cselect_b32 s29, s26, s30
	s_add_u32 s33, s30, 0x100
	s_addc_u32 s57, s31, 0
	s_add_u32 s30, s34, 0x80080
	v_mov_b64_e32 v[0:1], 0
	s_addc_u32 s31, s35, 0
	s_mov_b32 s58, -2
	v_mov_b64_e32 v[2:3], 0
	v_mov_b64_e32 v[4:5], 0
	v_mov_b64_e32 v[6:7], 0
	v_mov_b64_e32 v[16:17], 0
	v_mov_b64_e32 v[18:19], 0
	v_mov_b64_e32 v[20:21], 0
	v_mov_b64_e32 v[22:23], 0
	v_mov_b64_e32 v[32:33], 0
	v_mov_b64_e32 v[34:35], 0
	v_mov_b64_e32 v[36:37], 0
	v_mov_b64_e32 v[38:39], 0
	v_mov_b64_e32 v[48:49], 0
	v_mov_b64_e32 v[50:51], 0
	v_mov_b64_e32 v[52:53], 0
	v_mov_b64_e32 v[54:55], 0
	v_mov_b64_e32 v[8:9], 0
	v_mov_b64_e32 v[10:11], 0
	v_mov_b64_e32 v[12:13], 0
	v_mov_b64_e32 v[14:15], 0
	v_mov_b64_e32 v[24:25], 0
	v_mov_b64_e32 v[26:27], 0
	v_mov_b64_e32 v[28:29], 0
	v_mov_b64_e32 v[30:31], 0
	v_mov_b64_e32 v[40:41], 0
	v_mov_b64_e32 v[42:43], 0
	v_mov_b64_e32 v[44:45], 0
	v_mov_b64_e32 v[46:47], 0
	v_mov_b64_e32 v[56:57], 0
	v_mov_b64_e32 v[58:59], 0
	v_mov_b64_e32 v[60:61], 0
	v_mov_b64_e32 v[62:63], 0
	v_mov_b64_e32 v[64:65], 0
	v_mov_b64_e32 v[66:67], 0
	v_mov_b64_e32 v[68:69], 0
	v_mov_b64_e32 v[70:71], 0
	v_mov_b64_e32 v[80:81], 0
	v_mov_b64_e32 v[82:83], 0
	v_mov_b64_e32 v[84:85], 0
	v_mov_b64_e32 v[86:87], 0
	v_mov_b64_e32 v[96:97], 0
	v_mov_b64_e32 v[98:99], 0
	v_mov_b64_e32 v[100:101], 0
	v_mov_b64_e32 v[102:103], 0
	v_mov_b64_e32 v[112:113], 0
	v_mov_b64_e32 v[114:115], 0
	v_mov_b64_e32 v[116:117], 0
	v_mov_b64_e32 v[118:119], 0
	v_mov_b64_e32 v[72:73], 0
	v_mov_b64_e32 v[74:75], 0
	v_mov_b64_e32 v[76:77], 0
	v_mov_b64_e32 v[78:79], 0
	v_mov_b64_e32 v[88:89], 0
	v_mov_b64_e32 v[90:91], 0
	v_mov_b64_e32 v[92:93], 0
	v_mov_b64_e32 v[94:95], 0
	v_mov_b64_e32 v[104:105], 0
	v_mov_b64_e32 v[106:107], 0
	v_mov_b64_e32 v[108:109], 0
	v_mov_b64_e32 v[110:111], 0
	v_mov_b64_e32 v[120:121], 0
	v_mov_b64_e32 v[122:123], 0
	v_mov_b64_e32 v[124:125], 0
	v_mov_b64_e32 v[126:127], 0
	v_add_u32_e32 v248, 0x18000, v178
	v_add_u32_e32 v249, 0x1c000, v178
	s_cmp_lt_u32 s81, 4
	s_cbranch_scc0 .Lsp_skip8
	s_setprio 1
